# P2: next-chunk conv-row loads moved from post-barrier burst into attention epilogue; carry-in fold batched
# speedup vs baseline: 1.0223x; 1.0134x over previous
.LBB0_208:
	s_or_b64 exec, exec, s[0:1]
	v_readlane_b32 s0, v255, 19
	v_readlane_b32 s1, v255, 20
	s_and_b64 s[0:1], s[0:1], exec
	s_cselect_b32 s0, s96, s41
	s_lshl_b32 s0, s0, 7
	s_or_b32 s13, s0, s79
	v_add_u32_e32 v0, 0, v91
	v_or_b32_e32 v1, s13, v101
	s_waitcnt lgkmcnt(0)
	v_mad_u32_u24 v1, v1, s61, v0
	ds_read_b128 v[74:77], v1
	ds_read_b128 v[78:81], v1 offset:64
	s_and_b64 s[0:1], s[98:99], exec
	s_cselect_b32 s0, s96, s41
	s_lshl_b32 s14, s0, 7
	s_waitcnt vmcnt(17) lgkmcnt(1)
	v_mfma_f32_16x16x32_bf16 v[74:77], v[74:77], v[44:47], 0
	s_or_b32 s0, s77, s14
	v_or_b32_e32 v1, s0, v101
	s_and_b64 s[0:1], s[4:5], exec
	v_mad_u32_u24 v1, v1, s61, v0
	s_cselect_b32 s0, s96, s41
	s_waitcnt vmcnt(16) lgkmcnt(0)
	v_mfma_f32_16x16x32_bf16 v[74:77], v[78:81], v[40:43], v[74:77]
	ds_read_b128 v[78:81], v1
	ds_read_b128 v[82:85], v1 offset:64
	s_lshl_b32 s0, s0, 7
	s_or_b32 s11, s0, s36
	v_or_b32_e32 v1, s11, v101
	v_mad_u32_u24 v1, v1, s61, v0
	s_waitcnt lgkmcnt(1)
	v_mfma_f32_16x16x32_bf16 v[78:81], v[78:81], v[44:47], 0
	ds_read_b128 v[86:89], v1
	s_and_b64 s[0:1], s[26:27], exec
	s_cselect_b32 s0, s96, s41
	s_waitcnt lgkmcnt(1)
	v_mfma_f32_16x16x32_bf16 v[78:81], v[82:85], v[40:43], v[78:81]
	ds_read_b128 v[82:85], v1 offset:64
	s_lshl_b32 s12, s0, 7
	s_or_b32 s0, s72, s12
	s_waitcnt lgkmcnt(1)
	v_mfma_f32_16x16x32_bf16 v[86:89], v[86:89], v[44:47], 0
	v_or_b32_e32 v1, s0, v101
	s_and_b64 s[0:1], s[24:25], exec
	v_mad_u32_u24 v1, v1, s61, v0
	s_cselect_b32 s0, s96, s41
	s_waitcnt lgkmcnt(0)
	v_mfma_f32_16x16x32_bf16 v[82:85], v[82:85], v[40:43], v[86:89]
	s_nop 2
	ds_read_b128 v[86:89], v1
	ds_read_b128 v[106:109], v1 offset:64
	s_lshl_b32 s0, s0, 7
	s_or_b32 s9, s0, s43
	v_or_b32_e32 v1, s9, v101
	v_mad_u32_u24 v1, v1, s61, v0
	s_waitcnt lgkmcnt(1)
	v_mfma_f32_16x16x32_bf16 v[86:89], v[86:89], v[44:47], 0
	ds_read_b128 v[110:113], v1
	s_and_b64 s[0:1], s[28:29], exec
	s_cselect_b32 s0, s96, s41
	s_waitcnt lgkmcnt(1)
	v_mfma_f32_16x16x32_bf16 v[86:89], v[106:109], v[40:43], v[86:89]
	ds_read_b128 v[106:109], v1 offset:64
	s_lshl_b32 s10, s0, 7
	s_or_b32 s0, s47, s10
	s_waitcnt lgkmcnt(1)
	v_mfma_f32_16x16x32_bf16 v[110:113], v[110:113], v[44:47], 0
	v_or_b32_e32 v1, s0, v101
	s_and_b64 s[0:1], s[2:3], exec
	v_mad_u32_u24 v1, v1, s61, v0
	s_cselect_b32 s0, s96, s41
	s_waitcnt lgkmcnt(0)
	v_mfma_f32_16x16x32_bf16 v[106:109], v[106:109], v[40:43], v[110:113]
	s_nop 2
	ds_read_b128 v[110:113], v1
	ds_read_b128 v[114:117], v1 offset:64
	s_lshl_b32 s0, s0, 7
	s_or_b32 s7, s0, s49
	v_or_b32_e32 v1, s7, v101
	v_mad_u32_u24 v1, v1, s61, v0
	s_waitcnt lgkmcnt(1)
	v_mfma_f32_16x16x32_bf16 v[110:113], v[110:113], v[44:47], 0
	ds_read_b128 v[118:121], v1
	s_and_b64 s[0:1], s[30:31], exec
	s_cselect_b32 s0, s96, s41
	s_waitcnt lgkmcnt(1)
	v_mfma_f32_16x16x32_bf16 v[110:113], v[114:117], v[40:43], v[110:113]
	ds_read_b128 v[114:117], v1 offset:64
	s_lshl_b32 s8, s0, 7
	s_or_b32 s0, s76, s8
	s_waitcnt lgkmcnt(1)
	v_mfma_f32_16x16x32_bf16 v[118:121], v[118:121], v[44:47], 0
	v_or_b32_e32 v1, s0, v101
	s_and_b64 s[0:1], s[80:81], exec
	v_mad_u32_u24 v1, v1, s61, v0
	s_cselect_b32 s0, s96, s41
	s_waitcnt lgkmcnt(0)
	v_mfma_f32_16x16x32_bf16 v[114:117], v[114:117], v[40:43], v[118:121]
	s_nop 2
	ds_read_b128 v[118:121], v1
	ds_read_b128 v[122:125], v1 offset:64
	s_lshl_b32 s0, s0, 7
	s_or_b32 s6, s0, s73
	v_or_b32_e32 v1, s6, v101
	v_mad_u32_u24 v0, v1, s61, v0
	s_waitcnt lgkmcnt(1)
	v_mfma_f32_16x16x32_bf16 v[118:121], v[118:121], v[44:47], 0
	ds_read_b128 v[126:129], v0
	s_cmp_lg_u32 s54, 0
	s_cselect_b64 s[0:1], -1, 0
	s_waitcnt lgkmcnt(1)
	v_mfma_f32_16x16x32_bf16 v[118:121], v[122:125], v[40:43], v[118:121]
	ds_read_b128 v[122:125], v0 offset:64
	v_cmp_lt_i32_e32 vcc, s68, v105
	s_or_b64 s[16:17], s[0:1], vcc
	s_waitcnt lgkmcnt(1)
	v_mfma_f32_16x16x32_bf16 v[44:47], v[126:129], v[44:47], 0
	v_cmp_ge_u32_e32 vcc, v103, v101
	s_and_b64 vcc, s[16:17], vcc
	v_or_b32_e32 v0, 1, v105
	s_waitcnt lgkmcnt(0)
	v_mfma_f32_16x16x32_bf16 v[40:43], v[122:125], v[40:43], v[44:47]
	v_or_b32_e32 v1, 2, v105
	v_or_b32_e32 v2, 3, v105
	s_mov_b32 s15, 0xff800000
	v_cndmask_b32_e32 v45, v96, v74, vcc
	v_cmp_lt_i32_e32 vcc, s69, v105
	s_or_b64 s[16:17], s[0:1], vcc
	v_cmp_ge_i32_e32 vcc, v0, v90
	s_and_b64 vcc, s[16:17], vcc
	v_add_u32_e32 v44, 0x80, v90
	v_cndmask_b32_e32 v0, v96, v75, vcc
	v_cmp_lt_i32_e32 vcc, s68, v1
	s_or_b64 s[16:17], s[0:1], vcc
	v_cmp_ge_i32_e32 vcc, v1, v90
	s_and_b64 vcc, vcc, s[16:17]
	v_max3_f32 v46, v45, s15, v0
	v_cndmask_b32_e32 v1, v96, v76, vcc
	v_cmp_lt_i32_e32 vcc, s68, v2
	s_or_b64 s[16:17], s[0:1], vcc
	v_cmp_ge_i32_e32 vcc, v2, v90
	s_and_b64 vcc, vcc, s[16:17]
	v_and_b32_e32 v104, 24, v104
	v_cndmask_b32_e32 v47, v96, v77, vcc
	v_max3_f32 v2, v46, v1, v47
	v_or_b32_e32 v46, s71, v103
	v_cmp_lt_i32_e32 vcc, s68, v46
	s_or_b64 vcc, s[0:1], vcc
	v_or_b32_e32 v76, 2, v46
	v_cndmask_b32_e32 v74, v96, v78, vcc
	v_cmp_lt_i32_e32 vcc, s69, v46
	s_or_b64 vcc, s[0:1], vcc
	v_or_b32_e32 v46, 3, v46
	v_cndmask_b32_e32 v75, v96, v79, vcc
	v_cmp_lt_i32_e32 vcc, s68, v76
	s_or_b64 vcc, s[0:1], vcc
	v_or_b32_e32 v77, s74, v103
	v_cndmask_b32_e32 v76, v96, v80, vcc
	v_cmp_lt_i32_e32 vcc, s68, v46
	s_or_b64 vcc, s[0:1], vcc
	v_or_b32_e32 v80, 2, v77
	v_cndmask_b32_e32 v46, v96, v81, vcc
	v_cmp_lt_i32_e32 vcc, s68, v77
	s_or_b64 vcc, s[0:1], vcc
	v_or_b32_e32 v81, s37, v103
	v_cndmask_b32_e32 v78, v96, v82, vcc
	v_cmp_lt_i32_e32 vcc, s69, v77
	s_or_b64 vcc, s[0:1], vcc
	v_or_b32_e32 v77, 3, v77
	v_cndmask_b32_e32 v79, v96, v83, vcc
	v_cmp_lt_i32_e32 vcc, s68, v80
	s_or_b64 vcc, s[0:1], vcc
	v_or_b32_e32 v82, 2, v81
	v_cndmask_b32_e32 v80, v96, v84, vcc
	v_cmp_lt_i32_e32 vcc, s68, v77
	s_or_b64 vcc, s[0:1], vcc
	v_max3_f32 v2, v2, v74, v75
	v_cndmask_b32_e32 v77, v96, v85, vcc
	v_cmp_lt_i32_e32 vcc, s68, v81
	s_or_b64 vcc, s[0:1], vcc
	v_max3_f32 v2, v2, v76, v46
	v_cndmask_b32_e32 v90, v96, v86, vcc
	v_cmp_lt_i32_e32 vcc, s69, v81
	s_or_b64 vcc, s[0:1], vcc
	v_or_b32_e32 v81, 3, v81
	v_cndmask_b32_e32 v91, v96, v87, vcc
	v_cmp_lt_i32_e32 vcc, s68, v82
	s_or_b64 vcc, s[0:1], vcc
	v_max3_f32 v2, v2, v78, v79
	v_cndmask_b32_e32 v122, v96, v88, vcc
	v_cmp_lt_i32_e32 vcc, s68, v81
	s_or_b64 vcc, s[0:1], vcc
	v_or_b32_e32 v81, s42, v103
	v_cndmask_b32_e32 v123, v96, v89, vcc
	v_cmp_lt_i32_e32 vcc, s68, v81
	s_or_b64 vcc, s[0:1], vcc
	v_or_b32_e32 v82, 2, v81
	v_cndmask_b32_e32 v124, v96, v106, vcc
	v_cmp_lt_i32_e32 vcc, s69, v81
	s_or_b64 vcc, s[0:1], vcc
	v_or_b32_e32 v81, 3, v81
	v_cndmask_b32_e32 v125, v96, v107, vcc
	v_cmp_lt_i32_e32 vcc, s68, v82
	s_or_b64 vcc, s[0:1], vcc
	v_max3_f32 v2, v2, v80, v77
	v_cndmask_b32_e32 v126, v96, v108, vcc
	v_cmp_lt_i32_e32 vcc, s68, v81
	s_or_b64 vcc, s[0:1], vcc
	v_or_b32_e32 v81, s46, v103
	v_cndmask_b32_e32 v127, v96, v109, vcc
	v_cmp_lt_i32_e32 vcc, s68, v81
	s_or_b64 vcc, s[0:1], vcc
	v_or_b32_e32 v82, 2, v81
	v_cndmask_b32_e32 v128, v96, v110, vcc
	v_cmp_lt_i32_e32 vcc, s69, v81
	s_or_b64 vcc, s[0:1], vcc
	v_or_b32_e32 v81, 3, v81
	v_cndmask_b32_e32 v129, v96, v111, vcc
	v_cmp_lt_i32_e32 vcc, s68, v82
	s_or_b64 vcc, s[0:1], vcc
	v_max3_f32 v2, v2, v90, v91
	v_cndmask_b32_e32 v130, v96, v112, vcc
	v_cmp_lt_i32_e32 vcc, s68, v81
	s_or_b64 vcc, s[0:1], vcc
	v_or_b32_e32 v81, s48, v103
	v_cndmask_b32_e32 v131, v96, v113, vcc
	v_cmp_lt_i32_e32 vcc, s68, v81
	s_or_b64 vcc, s[0:1], vcc
	v_or_b32_e32 v82, 2, v81
	v_cndmask_b32_e32 v132, v96, v114, vcc
	v_cmp_lt_i32_e32 vcc, s69, v81
	s_or_b64 vcc, s[0:1], vcc
	v_or_b32_e32 v81, 3, v81
	v_cndmask_b32_e32 v115, v96, v115, vcc
	v_cmp_lt_i32_e32 vcc, s68, v82
	s_or_b64 vcc, s[0:1], vcc
	v_max3_f32 v2, v2, v122, v123
	v_cndmask_b32_e32 v133, v96, v116, vcc
	v_cmp_lt_i32_e32 vcc, s68, v81
	v_max3_f32 v2, v2, v124, v125
	s_or_b64 vcc, s[0:1], vcc
	v_or_b32_e32 v81, s62, v103
	v_max3_f32 v2, v2, v126, v127
	v_cndmask_b32_e32 v134, v96, v117, vcc
	v_cmp_lt_i32_e32 vcc, s68, v81
	v_max3_f32 v2, v2, v128, v129
	s_or_b64 vcc, s[0:1], vcc
	v_max3_f32 v2, v2, v130, v131
	v_cndmask_b32_e32 v112, v96, v118, vcc
	v_cmp_lt_i32_e32 vcc, s69, v81
	v_max3_f32 v2, v2, v132, v115
	s_or_b64 vcc, s[0:1], vcc
	v_max3_f32 v2, v2, v133, v134
	v_cndmask_b32_e32 v113, v96, v119, vcc
	v_max3_f32 v82, v2, v112, v113
	v_or_b32_e32 v2, 2, v81
	v_cmp_lt_i32_e32 vcc, s68, v2
	s_or_b64 vcc, s[0:1], vcc
	v_or_b32_e32 v2, 3, v81
	v_cndmask_b32_e32 v114, v96, v120, vcc
	v_cmp_lt_i32_e32 vcc, s68, v2
	s_or_b64 vcc, s[0:1], vcc
	v_lshrrev_b32_e32 v116, 2, v101
	v_cndmask_b32_e32 v2, v96, v121, vcc
	v_max3_f32 v81, v82, v114, v2
	v_or_b32_e32 v82, s67, v103
	v_cmp_lt_i32_e32 vcc, s68, v82
	s_or_b64 s[16:17], s[0:1], vcc
	v_cmp_le_i32_e32 vcc, v82, v44
	s_and_b64 vcc, s[16:17], vcc
	v_or_b32_e32 v116, v103, v116
	v_cndmask_b32_e32 v108, v96, v40, vcc
	v_cmp_lt_i32_e32 vcc, s69, v82
	s_or_b64 s[16:17], s[0:1], vcc
	v_cmp_lt_i32_e32 vcc, v82, v44
	s_and_b64 vcc, s[16:17], vcc
	v_mul_u32_u24_e32 v116, 0x90, v116
	v_cndmask_b32_e32 v109, v96, v41, vcc
	v_or_b32_e32 v41, 2, v82
	v_cmp_lt_i32_e32 vcc, s68, v41
	s_or_b64 s[16:17], s[0:1], vcc
	v_cmp_le_i32_e32 vcc, v41, v44
	s_and_b64 vcc, s[16:17], vcc
	v_or_b32_e32 v41, 3, v82
	v_cndmask_b32_e32 v110, v96, v42, vcc
	v_cmp_lt_i32_e32 vcc, s68, v41
	s_or_b64 s[0:1], s[0:1], vcc
	v_cmp_le_i32_e32 vcc, v41, v44
	v_and_b32_e32 v42, 64, v95
	s_and_b64 vcc, s[0:1], vcc
	v_xor_b32_e32 v41, 16, v95
	v_add_u32_e32 v42, 64, v42
	v_cndmask_b32_e32 v111, v96, v43, vcc
	v_cmp_lt_i32_e32 vcc, v41, v42
	v_max3_f32 v40, v81, v108, v109
	v_max3_f32 v40, v40, v110, v111
	v_cndmask_b32_e32 v41, v95, v41, vcc
	v_lshlrev_b32_e32 v105, 2, v41
	ds_bpermute_b32 v41, v105, v40
	s_or_b32 s0, s14, s50
	v_add3_u32 v104, 0, v116, v104
	s_mulk_i32 s13, 0x90
	s_mulk_i32 s0, 0x90
	s_waitcnt lgkmcnt(0)
	v_max_f32_e32 v41, v41, v41
	v_max_f32_e32 v40, v40, v41
	v_xor_b32_e32 v41, 32, v95
	v_cmp_lt_i32_e32 vcc, v41, v42
	s_mulk_i32 s11, 0x90
	s_mulk_i32 s9, 0x90
	v_cndmask_b32_e32 v41, v95, v41, vcc
	v_lshlrev_b32_e32 v106, 2, v41
	ds_bpermute_b32 v41, v106, v40
	s_mulk_i32 s7, 0x90
	s_mulk_i32 s6, 0x90
	s_waitcnt lgkmcnt(0)
	v_max_f32_e32 v41, v41, v41
	v_max_f32_e32 v40, v40, v41
	v_mul_f32_e32 v40, 0x3e38aa3b, v40
	v_max_f32_e32 v41, v53, v53
	v_max_f32_e32 v107, v40, v41
	v_fma_f32 v42, v74, s70, -v107
	v_fma_f32 v1, v1, s70, -v107
	v_exp_f32_e32 v82, v42
	v_fma_f32 v42, v75, s70, -v107
	v_exp_f32_e32 v88, v1
	v_fma_f32 v1, v47, s70, -v107
	v_exp_f32_e32 v83, v42
	v_fma_f32 v42, v76, s70, -v107
	v_exp_f32_e32 v89, v1
	v_exp_f32_e32 v84, v42
	v_fma_f32 v42, v46, s70, -v107
	v_fma_f32 v43, v80, s70, -v107
	v_exp_f32_e32 v85, v42
	v_exp_f32_e32 v80, v43
	v_fma_f32 v43, v77, s70, -v107
	v_exp_f32_e32 v81, v43
	v_fma_f32 v0, v0, s70, -v107
	v_exp_f32_e32 v87, v0
	v_pk_add_f32 v[0:1], v[88:89], 0 op_sel_hi:[1,0]
	v_fma_f32 v42, v78, s70, -v107
	v_exp_f32_e32 v74, v42
	v_fma_f32 v42, v79, s70, -v107
	v_pk_add_f32 v[0:1], v[84:85], v[0:1]
	v_exp_f32_e32 v75, v42
	v_pk_add_f32 v[42:43], v[80:81], v[0:1]
	v_fma_f32 v0, v90, s70, -v107
	v_exp_f32_e32 v76, v0
	v_fma_f32 v0, v91, s70, -v107
	v_exp_f32_e32 v77, v0
	v_fma_f32 v0, v122, s70, -v107
	v_exp_f32_e32 v78, v0
	v_fma_f32 v0, v123, s70, -v107
	v_fma_f32 v40, v45, s70, -v107
	v_exp_f32_e32 v79, v0
	v_fma_f32 v44, v126, s70, -v107
	v_fma_f32 v45, v127, s70, -v107
	v_exp_f32_e32 v44, v44
	v_exp_f32_e32 v45, v45
	v_exp_f32_e32 v86, v40
	v_pk_add_f32 v[42:43], v[78:79], v[42:43]
	v_fma_f32 v0, v124, s70, -v107
	v_fma_f32 v1, v125, s70, -v107
	v_pk_add_f32 v[46:47], v[44:45], v[42:43]
	v_fma_f32 v42, v130, s70, -v107
	v_add_u32_e32 v126, s13, v104
	v_add_u32_e32 v130, s0, v104
	v_pk_add_f32 v[40:41], v[86:87], 0 op_sel_hi:[1,0]
	v_exp_f32_e32 v0, v0
	v_exp_f32_e32 v1, v1
	ds_read_b64_tr_b16 v[116:117], v126 offset:36864
	ds_read_b64_tr_b16 v[118:119], v130 offset:36864
	v_pk_add_f32 v[40:41], v[82:83], v[40:41]
	v_fma_f32 v43, v131, s70, -v107
	v_pk_add_f32 v[40:41], v[74:75], v[40:41]
	s_or_b32 s0, s12, s51
	v_pk_add_f32 v[40:41], v[76:77], v[40:41]
	s_mulk_i32 s0, 0x90
	v_pk_add_f32 v[90:91], v[0:1], v[40:41]
	v_fma_f32 v40, v128, s70, -v107
	v_fma_f32 v41, v129, s70, -v107
	ds_read_b64_tr_b16 v[122:123], v130 offset:36896
	ds_read_b64_tr_b16 v[120:121], v126 offset:36896
	ds_read_b64_tr_b16 v[124:125], v126 offset:36928
	ds_read_b64_tr_b16 v[128:129], v126 offset:36960
	ds_read_b64_tr_b16 v[126:127], v130 offset:36928
	ds_read_b64_tr_b16 v[130:131], v130 offset:36960
	v_cvt_pk_bf16_f32 v86, v86, v87
	v_cvt_pk_bf16_f32 v87, v88, v89
	v_cvt_pk_bf16_f32 v88, v82, v83
	v_cvt_pk_bf16_f32 v89, v84, v85
	v_fma_f32 v83, v115, s70, -v107
	v_add_u32_e32 v115, s11, v104
	v_add_u32_e32 v138, s0, v104
	s_waitcnt lgkmcnt(6)
	v_mfma_f32_16x16x32_bf16 v[116:119], v[116:119], v[86:89], 0
	v_fma_f32 v82, v132, s70, -v107
	v_fma_f32 v84, v133, s70, -v107
	v_fma_f32 v85, v134, s70, -v107
	s_waitcnt lgkmcnt(4)
	v_mfma_f32_16x16x32_bf16 v[120:123], v[120:123], v[86:89], 0
	v_cvt_pk_bf16_f32 v74, v74, v75
	v_cvt_pk_bf16_f32 v75, v80, v81
	v_cvt_pk_bf16_f32 v76, v76, v77
	s_waitcnt lgkmcnt(1)
	v_mfma_f32_16x16x32_bf16 v[124:127], v[124:127], v[86:89], 0
	v_cvt_pk_bf16_f32 v77, v78, v79
	v_fma_f32 v112, v112, s70, -v107
	s_or_b32 s0, s10, s33
	s_waitcnt lgkmcnt(0)
	v_mfma_f32_16x16x32_bf16 v[86:89], v[128:131], v[86:89], 0
	ds_read_b64_tr_b16 v[128:129], v115 offset:36864
	ds_read_b64_tr_b16 v[130:131], v138 offset:36864
	ds_read_b64_tr_b16 v[80:81], v138 offset:36896
	ds_read_b64_tr_b16 v[78:79], v115 offset:36896
	ds_read_b64_tr_b16 v[132:133], v115 offset:36928
	ds_read_b64_tr_b16 v[136:137], v115 offset:36960
	ds_read_b64_tr_b16 v[134:135], v138 offset:36928
	ds_read_b64_tr_b16 v[138:139], v138 offset:36960
	v_exp_f32_e32 v140, v112
	v_fma_f32 v112, v113, s70, -v107
	s_mulk_i32 s0, 0x90
	s_waitcnt lgkmcnt(6)
	v_mfma_f32_16x16x32_bf16 v[116:119], v[128:131], v[74:77], v[116:119]
	v_exp_f32_e32 v141, v112
	v_fma_f32 v112, v114, s70, -v107
	v_exp_f32_e32 v40, v40
	s_waitcnt lgkmcnt(4)
	v_mfma_f32_16x16x32_bf16 v[78:81], v[78:81], v[74:77], v[120:123]
	v_exp_f32_e32 v41, v41
	v_exp_f32_e32 v42, v42
	v_exp_f32_e32 v43, v43
	s_waitcnt lgkmcnt(1)
	v_mfma_f32_16x16x32_bf16 v[120:123], v[132:135], v[74:77], v[124:127]
	v_exp_f32_e32 v132, v112
	v_exp_f32_e32 v82, v82
	v_exp_f32_e32 v83, v83
	s_waitcnt lgkmcnt(0)
	v_mfma_f32_16x16x32_bf16 v[74:77], v[136:139], v[74:77], v[86:89]
	v_add_f32_e64 v90, v40, v90
	v_add_f32_e64 v91, v41, v91
	v_pk_add_f32 v[46:47], v[42:43], v[46:47]
	v_exp_f32_e32 v84, v84
	v_cvt_pk_bf16_f32 v86, v0, v1
	v_add_u32_e32 v0, s9, v104
	v_add_u32_e32 v1, s0, v104
	ds_read_b64_tr_b16 v[112:113], v0 offset:36864
	ds_read_b64_tr_b16 v[114:115], v1 offset:36864
	v_cvt_pk_bf16_f32 v88, v40, v41
	v_cvt_pk_bf16_f32 v89, v42, v43
	ds_read_b64_tr_b16 v[42:43], v1 offset:36896
	ds_read_b64_tr_b16 v[40:41], v0 offset:36896
	ds_read_b64_tr_b16 v[124:125], v0 offset:36928
	ds_read_b64_tr_b16 v[128:129], v0 offset:36960
	ds_read_b64_tr_b16 v[126:127], v1 offset:36928
	ds_read_b64_tr_b16 v[130:131], v1 offset:36960
	s_or_b32 s0, s8, s35
	v_exp_f32_e32 v85, v85
	v_pk_add_f32 v[90:91], v[82:83], v[90:91]
	v_cvt_pk_bf16_f32 v87, v44, v45
	v_fma_f32 v0, v2, s70, -v107
	v_fma_f32 v2, v108, s70, -v107
	v_fma_f32 v44, v110, s70, -v107
	s_mulk_i32 s0, 0x90
	v_exp_f32_e32 v133, v0
	v_pk_add_f32 v[0:1], v[140:141], v[90:91]
	s_waitcnt lgkmcnt(4)
	v_mfma_f32_16x16x32_bf16 v[40:43], v[40:43], v[86:89], v[78:81]
	v_exp_f32_e32 v90, v2
	v_fma_f32 v2, v109, s70, -v107
	v_add_u32_e32 v45, s7, v104
	s_waitcnt lgkmcnt(1)
	v_mfma_f32_16x16x32_bf16 v[78:81], v[124:127], v[86:89], v[120:123]
	v_exp_f32_e32 v124, v44
	v_fma_f32 v44, v111, s70, -v107
	v_add_u32_e32 v91, s0, v104
	v_mfma_f32_16x16x32_bf16 v[112:115], v[112:115], v[86:89], v[116:119]
	v_exp_f32_e32 v125, v44
	v_pk_add_f32 v[46:47], v[84:85], v[46:47]
	s_and_b64 s[0:1], s[52:53], exec
	s_waitcnt lgkmcnt(0)
	v_mfma_f32_16x16x32_bf16 v[74:77], v[128:131], v[86:89], v[74:77]
	ds_read_b64_tr_b16 v[86:87], v45 offset:36864
	ds_read_b64_tr_b16 v[88:89], v91 offset:36864
	ds_read_b64_tr_b16 v[110:111], v91 offset:36896
	ds_read_b64_tr_b16 v[108:109], v45 offset:36896
	ds_read_b64_tr_b16 v[116:117], v45 offset:36928
	ds_read_b64_tr_b16 v[120:121], v45 offset:36960
	ds_read_b64_tr_b16 v[118:119], v91 offset:36928
	ds_read_b64_tr_b16 v[122:123], v91 offset:36960
	v_exp_f32_e32 v91, v2
	v_cvt_pk_bf16_f32 v82, v82, v83
	v_cvt_pk_bf16_f32 v83, v84, v85
	v_cvt_pk_bf16_f32 v84, v140, v141
	v_cvt_pk_bf16_f32 v85, v132, v133
	v_pk_add_f32 v[44:45], v[132:133], v[46:47]
	s_cselect_b32 s0, s96, s41
	s_waitcnt lgkmcnt(4)
	v_mfma_f32_16x16x32_bf16 v[40:43], v[108:111], v[82:85], v[40:43]
	v_add_f32_e64 v108, v124, v44
	v_add_f32_e64 v109, v125, v45
	v_pk_add_f32 v[0:1], v[90:91], v[0:1]
	s_lshl_b32 s0, s0, 7
	v_pk_mov_b32 v[110:111], v[0:1], v[108:109] op_sel:[1,0]
	v_mov_b32_e32 v1, v109
	s_or_b32 s0, s0, s75
	v_pk_add_f32 v[0:1], v[110:111], v[0:1]
	s_mulk_i32 s0, 0x90
	s_waitcnt lgkmcnt(1)
	v_mfma_f32_16x16x32_bf16 v[44:47], v[116:119], v[82:85], v[78:81]
	v_add_f32_e32 v116, v0, v1
	v_cvt_pk_bf16_f32 v0, v90, v91
	v_add_u32_e32 v90, s6, v104
	v_add_u32_e32 v91, s0, v104
	ds_read_b64_tr_b16 v[78:79], v90 offset:36864
	ds_read_b64_tr_b16 v[80:81], v91 offset:36864
	v_mfma_f32_16x16x32_bf16 v[86:89], v[86:89], v[82:85], v[112:115]
	v_cvt_pk_bf16_f32 v1, v124, v125
	v_mov_b32_e32 v2, v3
	s_waitcnt vmcnt(7)
	v_and_b32_e32 v104, 0xffff0000, v70
	s_waitcnt lgkmcnt(2)
	v_mfma_f32_16x16x32_bf16 v[74:77], v[120:123], v[82:85], v[74:77]
	ds_read_b64_tr_b16 v[84:85], v91 offset:36896
	ds_read_b64_tr_b16 v[82:83], v90 offset:36896
	ds_read_b64_tr_b16 v[108:109], v90 offset:36928
	ds_read_b64_tr_b16 v[112:113], v90 offset:36960
	ds_read_b64_tr_b16 v[110:111], v91 offset:36928
	ds_read_b64_tr_b16 v[114:115], v91 offset:36960
	v_lshlrev_b32_e32 v90, 16, v70
	v_mul_f32_e32 v90, 0xbfb8aa3b, v90
	s_waitcnt lgkmcnt(6)
	v_mfma_f32_16x16x32_bf16 v[78:81], v[78:81], v[0:3], v[86:89]
	v_exp_f32_e32 v90, v90
	s_add_i32 s40, s40, 1
	s_nop 0
	ds_bpermute_b32 v86, v105, v116
	s_waitcnt lgkmcnt(5)
	v_mfma_f32_16x16x32_bf16 v[82:85], v[82:85], v[0:3], v[40:43]
	s_waitcnt vmcnt(3)
	v_lshlrev_b32_e32 v88, 16, v73
	v_and_b32_e32 v89, 0xffff0000, v73
	v_lshlrev_b32_e32 v105, 16, v71
	s_waitcnt lgkmcnt(0)
	v_add_f32_e32 v40, v116, v86
	ds_bpermute_b32 v41, v106, v40
	v_sub_f32_e32 v42, v53, v107
	v_exp_f32_e32 v42, v42
	v_mfma_f32_16x16x32_bf16 v[44:47], v[108:111], v[0:3], v[44:47]
	v_and_b32_e32 v106, 0xffff0000, v69
	s_waitcnt lgkmcnt(0)
	v_add_f32_e32 v40, v40, v41
	v_add_f32_e32 v86, v42, v40
	v_mfma_f32_16x16x32_bf16 v[40:43], v[112:115], v[0:3], v[74:77]
	v_lshl_add_u32 v1, v103, 2, v102
	v_lshlrev_b32_e32 v2, 16, v68
	v_lshlrev_b32_e32 v102, 16, v69
	v_add_u32_e32 v74, s38, v101
	s_mov_b32 s100, 0x9f57000
	v_lshl_add_u64 v[22:23], v[20:21], 0, s[100:101]
	global_load_dwordx4 v[28:31], v[22:23], off offset:3072
	v_and_b32_e32 v101, 0xffff0000, v68
	v_lshlrev_b32_e32 v68, 16, v72
	v_and_b32_e32 v69, 0xffff0000, v72
	v_pk_mul_f32 v[72:73], v[68:69], v[68:69]
	v_mul_f32_e32 v2, 0xbfb8aa3b, v2
	v_fmamk_f32 v72, v72, 0xbdd2d3e7, v93
	v_mul_f32_e32 v72, v72, v68
	v_exp_f32_e32 v2, v2
	v_exp_f32_e32 v91, v72
	v_mul_f32_e32 v72, 0xbfb8aa3b, v101
	v_fmamk_f32 v73, v73, 0xbdd2d3e7, v93
	v_and_b32_e32 v107, 0xffff0000, v71
	v_pk_mul_f32 v[70:71], v[88:89], v[88:89]
	v_exp_f32_e32 v101, v72
	v_mul_f32_e32 v72, 0xbfb8aa3b, v104
	v_mul_f32_e32 v73, v73, v69
	v_exp_f32_e32 v72, v72
	v_exp_f32_e32 v73, v73
	v_fmamk_f32 v70, v70, 0xbdd2d3e7, v93
	v_mul_f32_e32 v102, 0xbfb8aa3b, v102
	v_mul_f32_e32 v104, 0xbfb8aa3b, v105
	v_mul_f32_e32 v70, v70, v88
	v_exp_f32_e32 v102, v102
	v_exp_f32_e32 v104, v104
	v_exp_f32_e32 v105, v70
	v_mul_f32_e32 v70, 0xbfb8aa3b, v106
	v_fmamk_f32 v71, v71, 0xbdd2d3e7, v93
	v_add_f32_e32 v2, 1.0, v2
	v_pk_add_f32 v[90:91], v[90:91], 1.0 op_sel_hi:[1,0]
	v_exp_f32_e32 v109, v70
	v_mul_f32_e32 v70, 0xbfb8aa3b, v107
	v_mul_f32_e32 v71, v71, v89
	v_rcp_f32_e32 v106, v2
	v_mul_f32_e32 v2, v90, v91
	v_exp_f32_e32 v70, v70
	v_exp_f32_e32 v71, v71
	v_rcp_f32_e32 v90, v2
	v_add_f32_e32 v2, 1.0, v101
	v_pk_add_f32 v[72:73], v[72:73], 1.0 op_sel_hi:[1,0]
	v_rcp_f32_e32 v107, v2
	v_mul_f32_e32 v2, v72, v73
	v_ashrrev_i32_e32 v75, 31, v74
	v_rcp_f32_e32 v91, v2
	v_add_f32_e32 v2, 1.0, v102
	v_pk_add_f32 v[72:73], v[104:105], 1.0 op_sel_hi:[1,0]
	v_lshlrev_b64 v[74:75], 11, v[74:75]
	v_rcp_f32_e32 v108, v2
	v_mul_f32_e32 v2, v72, v73
	v_rcp_f32_e32 v0, v86
	v_lshl_add_u64 v[86:87], s[44:45], 0, v[74:75]
	ds_read_b128 v[74:77], v1
	v_rcp_f32_e32 v104, v2
	v_add_f32_e32 v2, 1.0, v109
	v_pk_add_f32 v[70:71], v[70:71], 1.0 op_sel_hi:[1,0]
	v_rcp_f32_e32 v109, v2
	v_mul_f32_e32 v2, v70, v71
	v_rcp_f32_e32 v105, v2
	ds_read_b128 v[70:73], v1 offset:64
	s_waitcnt lgkmcnt(1)
	v_pk_mul_f32 v[76:77], v[76:77], v[88:89]
	v_pk_mul_f32 v[68:69], v[74:75], v[68:69]
	v_pk_mul_f32 v[80:81], v[0:1], v[80:81] op_sel_hi:[0,1]
	v_pk_mul_f32 v[78:79], v[0:1], v[78:79] op_sel_hi:[0,1]
	v_pk_mul_f32 v[68:69], v[90:91], v[68:69]
	v_pk_mul_f32 v[74:75], v[104:105], v[76:77]
	v_pk_fma_f32 v[68:69], v[106:107], v[78:79], v[68:69]
	v_pk_fma_f32 v[74:75], v[108:109], v[80:81], v[74:75]
	v_lshlrev_b32_e32 v2, 1, v103
	v_cvt_pk_bf16_f32 v76, v68, v69
	v_cvt_pk_bf16_f32 v77, v74, v75
	v_lshl_add_u64 v[68:69], v[86:87], 0, v[2:3]
	global_store_dwordx2 v[68:69], v[76:77], off
	v_pk_mul_f32 v[74:75], v[0:1], v[84:85] op_sel_hi:[0,1]
	v_pk_mul_f32 v[76:77], v[0:1], v[82:83] op_sel_hi:[0,1]
	v_lshlrev_b32_e32 v2, 16, v62
	v_and_b32_e32 v82, 0xffff0000, v62
	v_lshlrev_b32_e32 v83, 16, v63
	v_and_b32_e32 v84, 0xffff0000, v63
	s_waitcnt vmcnt(4)
	v_lshlrev_b32_e32 v62, 16, v66
	v_and_b32_e32 v63, 0xffff0000, v66
	v_pk_mul_f32 v[78:79], v[62:63], v[62:63]
	v_lshlrev_b32_e32 v80, 16, v64
	v_fmamk_f32 v78, v78, 0xbdd2d3e7, v93
	v_mul_f32_e32 v2, 0xbfb8aa3b, v2
	v_mul_f32_e32 v80, 0xbfb8aa3b, v80
	v_mul_f32_e32 v78, v78, v62
	v_and_b32_e32 v85, 0xffff0000, v64
	v_lshlrev_b32_e32 v86, 16, v65
	v_and_b32_e32 v87, 0xffff0000, v65
	s_mov_b32 s100, 0x9f5a000
	v_lshl_add_u64 v[24:25], v[20:21], 0, s[100:101]
	global_load_dwordx4 v[24:27], v[24:25], off offset:2048
	v_lshlrev_b32_e32 v64, 16, v67
	v_and_b32_e32 v65, 0xffff0000, v67
	v_exp_f32_e32 v2, v2
	v_exp_f32_e32 v80, v80
	v_exp_f32_e32 v81, v78
	v_mul_f32_e32 v78, 0xbfb8aa3b, v82
	v_fmamk_f32 v79, v79, 0xbdd2d3e7, v93
	v_pk_mul_f32 v[66:67], v[64:65], v[64:65]
	v_exp_f32_e32 v88, v78
	v_mul_f32_e32 v78, 0xbfb8aa3b, v85
	v_mul_f32_e32 v79, v79, v63
	v_exp_f32_e32 v78, v78
	v_exp_f32_e32 v79, v79
	v_mul_f32_e32 v82, 0xbfb8aa3b, v83
	v_fmamk_f32 v66, v66, 0xbdd2d3e7, v93
	v_exp_f32_e32 v89, v82
	v_mul_f32_e32 v82, 0xbfb8aa3b, v86
	v_mul_f32_e32 v66, v66, v64
	v_exp_f32_e32 v82, v82
	v_exp_f32_e32 v83, v66
	v_mul_f32_e32 v66, 0xbfb8aa3b, v84
	v_fmamk_f32 v67, v67, 0xbdd2d3e7, v93
	v_add_f32_e32 v2, 1.0, v2
	v_pk_add_f32 v[80:81], v[80:81], 1.0 op_sel_hi:[1,0]
	v_exp_f32_e32 v86, v66
	v_mul_f32_e32 v66, 0xbfb8aa3b, v87
	v_mul_f32_e32 v67, v67, v65
	v_rcp_f32_e32 v84, v2
	v_mul_f32_e32 v2, v80, v81
	v_exp_f32_e32 v66, v66
	v_exp_f32_e32 v67, v67
	v_rcp_f32_e32 v80, v2
	v_add_f32_e32 v2, 1.0, v88
	v_pk_add_f32 v[78:79], v[78:79], 1.0 op_sel_hi:[1,0]
	v_rcp_f32_e32 v85, v2
	v_mul_f32_e32 v2, v78, v79
	v_rcp_f32_e32 v81, v2
	v_add_f32_e32 v2, 1.0, v89
	v_pk_add_f32 v[82:83], v[82:83], 1.0 op_sel_hi:[1,0]
	v_rcp_f32_e32 v78, v2
	v_mul_f32_e32 v2, v82, v83
	v_rcp_f32_e32 v82, v2
	v_add_f32_e32 v2, 1.0, v86
	v_pk_add_f32 v[66:67], v[66:67], 1.0 op_sel_hi:[1,0]
	v_rcp_f32_e32 v79, v2
	v_mul_f32_e32 v2, v66, v67
	v_rcp_f32_e32 v83, v2
	s_waitcnt lgkmcnt(0)
	v_pk_mul_f32 v[64:65], v[72:73], v[64:65]
	v_lshlrev_b32_e32 v2, 16, v56
	v_and_b32_e32 v72, 0xffff0000, v56
	v_pk_mul_f32 v[64:65], v[82:83], v[64:65]
	v_lshlrev_b32_e32 v73, 16, v57
	v_pk_fma_f32 v[64:65], v[78:79], v[74:75], v[64:65]
	v_and_b32_e32 v74, 0xffff0000, v57
	s_waitcnt vmcnt(4)
	v_lshlrev_b32_e32 v56, 16, v60
	v_and_b32_e32 v57, 0xffff0000, v60
	v_pk_mul_f32 v[66:67], v[0:1], v[46:47] op_sel_hi:[0,1]
	v_pk_mul_f32 v[46:47], v[56:57], v[56:57]
	v_pk_mul_f32 v[62:63], v[70:71], v[62:63]
	v_lshlrev_b32_e32 v75, 16, v58
	v_fmamk_f32 v46, v46, 0xbdd2d3e7, v93
	v_pk_mul_f32 v[62:63], v[80:81], v[62:63]
	v_mul_f32_e32 v2, 0xbfb8aa3b, v2
	v_mul_f32_e32 v60, 0xbfb8aa3b, v75
	v_mul_f32_e32 v46, v46, v56
	v_pk_fma_f32 v[62:63], v[84:85], v[76:77], v[62:63]
	v_and_b32_e32 v76, 0xffff0000, v58
	v_lshlrev_b32_e32 v77, 16, v59
	v_and_b32_e32 v78, 0xffff0000, v59
	v_lshlrev_b32_e32 v58, 16, v61
	v_and_b32_e32 v59, 0xffff0000, v61
	v_exp_f32_e32 v2, v2
	v_exp_f32_e32 v60, v60
	s_mov_b32 s100, 0x9f5d000
	v_lshl_add_u64 v[22:23], v[20:21], 0, s[100:101]
	global_load_dwordx4 v[36:39], v[22:23], off offset:1024
	v_exp_f32_e32 v61, v46
	v_mul_f32_e32 v46, 0xbfb8aa3b, v72
	v_fmamk_f32 v47, v47, 0xbdd2d3e7, v93
	v_pk_mul_f32 v[70:71], v[0:1], v[44:45] op_sel_hi:[0,1]
	v_pk_mul_f32 v[44:45], v[58:59], v[58:59]
	v_exp_f32_e32 v75, v46
	v_mul_f32_e32 v46, 0xbfb8aa3b, v76
	v_mul_f32_e32 v47, v47, v57
	v_exp_f32_e32 v46, v46
	v_exp_f32_e32 v47, v47
	v_mul_f32_e32 v72, 0xbfb8aa3b, v73
	v_fmamk_f32 v44, v44, 0xbdd2d3e7, v93
	v_exp_f32_e32 v76, v72
	v_mul_f32_e32 v72, 0xbfb8aa3b, v77
	v_mul_f32_e32 v44, v44, v58
	v_exp_f32_e32 v72, v72
	v_exp_f32_e32 v73, v44
	v_mul_f32_e32 v44, 0xbfb8aa3b, v74
	v_fmamk_f32 v45, v45, 0xbdd2d3e7, v93
	v_add_f32_e32 v2, 1.0, v2
	v_pk_add_f32 v[60:61], v[60:61], 1.0 op_sel_hi:[1,0]
	v_exp_f32_e32 v77, v44
	v_mul_f32_e32 v44, 0xbfb8aa3b, v78
	v_mul_f32_e32 v45, v45, v59
	v_rcp_f32_e32 v74, v2
	v_mul_f32_e32 v2, v60, v61
	v_exp_f32_e32 v44, v44
	v_exp_f32_e32 v45, v45
	v_rcp_f32_e32 v60, v2
	v_add_f32_e32 v2, 1.0, v75
	v_pk_add_f32 v[46:47], v[46:47], 1.0 op_sel_hi:[1,0]
	v_rcp_f32_e32 v75, v2
	v_mul_f32_e32 v2, v46, v47
	v_rcp_f32_e32 v61, v2
	v_add_f32_e32 v2, 1.0, v76
	v_pk_add_f32 v[46:47], v[72:73], 1.0 op_sel_hi:[1,0]
	v_cvt_pk_bf16_f32 v62, v62, v63
	v_cvt_pk_bf16_f32 v63, v64, v65
	v_rcp_f32_e32 v76, v2
	v_mul_f32_e32 v2, v46, v47
	global_store_dwordx2 v[68:69], v[62:63], off offset:32
	ds_read_b128 v[62:65], v1 offset:128
	v_rcp_f32_e32 v72, v2
	v_add_f32_e32 v2, 1.0, v77
	v_pk_add_f32 v[44:45], v[44:45], 1.0 op_sel_hi:[1,0]
	v_rcp_f32_e32 v77, v2
	v_mul_f32_e32 v2, v44, v45
	v_rcp_f32_e32 v73, v2
	ds_read_b128 v[44:47], v1 offset:192
	s_waitcnt lgkmcnt(1)
	v_pk_mul_f32 v[58:59], v[64:65], v[58:59]
	v_pk_mul_f32 v[56:57], v[62:63], v[56:57]
	v_pk_mul_f32 v[58:59], v[72:73], v[58:59]
	v_pk_mul_f32 v[56:57], v[60:61], v[56:57]
	v_pk_fma_f32 v[58:59], v[76:77], v[66:67], v[58:59]
	v_pk_fma_f32 v[56:57], v[74:75], v[70:71], v[56:57]
	v_pk_mul_f32 v[42:43], v[0:1], v[42:43] op_sel_hi:[0,1]
	v_pk_mul_f32 v[0:1], v[0:1], v[40:41] op_sel_hi:[0,1]
	s_waitcnt vmcnt(5)
	v_lshlrev_b32_e32 v40, 16, v54
	s_mov_b32 s100, s66
	v_lshl_add_u64 v[32:33], v[20:21], 0, s[100:101]
	global_load_dwordx4 v[32:35], v[32:33], off
	v_and_b32_e32 v41, 0xffff0000, v54
	v_cvt_pk_bf16_f32 v56, v56, v57
	v_cvt_pk_bf16_f32 v57, v58, v59
	v_lshlrev_b32_e32 v2, 16, v48
	v_and_b32_e32 v58, 0xffff0000, v48
	v_lshlrev_b32_e32 v59, 16, v49
	v_and_b32_e32 v60, 0xffff0000, v49
	v_lshlrev_b32_e32 v48, 16, v55
	v_and_b32_e32 v49, 0xffff0000, v55
	v_pk_mul_f32 v[54:55], v[40:41], v[40:41]
	global_store_dwordx2 v[68:69], v[56:57], off offset:64
	v_lshlrev_b32_e32 v56, 16, v50
	v_fmamk_f32 v54, v54, 0xbdd2d3e7, v93
	v_mul_f32_e32 v2, 0xbfb8aa3b, v2
	v_mul_f32_e32 v56, 0xbfb8aa3b, v56
	v_mul_f32_e32 v54, v54, v40
	v_and_b32_e32 v61, 0xffff0000, v50
	v_exp_f32_e32 v2, v2
	v_exp_f32_e32 v56, v56
	v_exp_f32_e32 v57, v54
	v_mul_f32_e32 v54, 0xbfb8aa3b, v58
	v_fmamk_f32 v55, v55, 0xbdd2d3e7, v93
	v_lshlrev_b32_e32 v62, 16, v51
	v_and_b32_e32 v63, 0xffff0000, v51
	v_pk_mul_f32 v[50:51], v[48:49], v[48:49]
	v_exp_f32_e32 v64, v54
	v_mul_f32_e32 v54, 0xbfb8aa3b, v61
	v_mul_f32_e32 v55, v55, v41
	v_exp_f32_e32 v54, v54
	v_exp_f32_e32 v55, v55
	v_mul_f32_e32 v58, 0xbfb8aa3b, v59
	v_fmamk_f32 v50, v50, 0xbdd2d3e7, v93
	v_exp_f32_e32 v65, v58
	v_mul_f32_e32 v58, 0xbfb8aa3b, v62
	v_mul_f32_e32 v50, v50, v48
	v_exp_f32_e32 v58, v58
	v_exp_f32_e32 v59, v50
	v_mul_f32_e32 v50, 0xbfb8aa3b, v60
	v_fmamk_f32 v51, v51, 0xbdd2d3e7, v93
	v_add_f32_e32 v2, 1.0, v2
	v_pk_add_f32 v[56:57], v[56:57], 1.0 op_sel_hi:[1,0]
	v_exp_f32_e32 v62, v50
	v_mul_f32_e32 v50, 0xbfb8aa3b, v63
	v_mul_f32_e32 v51, v51, v49
	v_rcp_f32_e32 v60, v2
	s_mov_b32 s100, 0x9f62000
	v_lshl_add_u64 v[20:21], v[20:21], 0, s[100:101]
	global_load_dwordx4 v[20:23], v[20:21], off offset:3072
	v_mul_f32_e32 v2, v56, v57
	v_exp_f32_e32 v50, v50
	v_exp_f32_e32 v51, v51
	v_rcp_f32_e32 v56, v2
	v_add_f32_e32 v2, 1.0, v64
	v_pk_add_f32 v[54:55], v[54:55], 1.0 op_sel_hi:[1,0]
	v_rcp_f32_e32 v61, v2
	v_mul_f32_e32 v2, v54, v55
	v_rcp_f32_e32 v57, v2
	v_add_f32_e32 v2, 1.0, v65
	v_pk_add_f32 v[58:59], v[58:59], 1.0 op_sel_hi:[1,0]
	v_rcp_f32_e32 v54, v2
	v_mul_f32_e32 v2, v58, v59
	v_rcp_f32_e32 v58, v2
	v_add_f32_e32 v2, 1.0, v62
	v_pk_add_f32 v[50:51], v[50:51], 1.0 op_sel_hi:[1,0]
	v_rcp_f32_e32 v55, v2
	v_mul_f32_e32 v2, v50, v51
	v_rcp_f32_e32 v59, v2
	s_waitcnt lgkmcnt(0)
	v_pk_mul_f32 v[46:47], v[46:47], v[48:49]
	v_pk_mul_f32 v[40:41], v[44:45], v[40:41]
	s_addk_i32 s38, 0x80
	v_pk_mul_f32 v[40:41], v[56:57], v[40:41]
	v_pk_mul_f32 v[44:45], v[58:59], v[46:47]
	v_pk_fma_f32 v[0:1], v[60:61], v[0:1], v[40:41]
	v_pk_fma_f32 v[42:43], v[54:55], v[42:43], v[44:45]
	v_cvt_pk_bf16_f32 v0, v0, v1
	v_cvt_pk_bf16_f32 v1, v42, v43
	global_store_dwordx2 v[68:69], v[0:1], off offset:96
	s_waitcnt lgkmcnt(0)
	s_barrier
	s_add_u32 s54, s54, 0x160000
	s_addc_u32 s55, s55, 0
	s_cmp_eq_u32 s54, 0x1600000
	s_cbranch_scc1 .LBB0_281
.LBB0_209:
	v_mov_b32_e32 v0, v52
	v_readlane_b32 s0, v255, 8
	v_and_b32_e32 v101, 15, v0
	v_lshlrev_b32_e32 v104, 3, v0
	v_bfe_u32 v88, v0, 4, 2
	v_lshrrev_b32_e32 v1, 2, v0
	v_and_b32_e32 v54, 56, v104
	v_ashrrev_i32_e32 v48, 3, v0
	v_add_u32_e32 v0, 0x200, v0
	v_or_b32_e32 v90, s34, v101
	v_or_b32_e32 v2, s0, v54
	v_ashrrev_i32_e32 v57, 3, v0
	v_mul_lo_u32 v0, v90, s60
	v_readlane_b32 s0, v255, 9
	s_and_b32 s41, s40, 1
	v_lshlrev_b32_e32 v91, 4, v88
	v_add_lshl_u32 v56, v0, s0, 1
	s_add_u32 s0, s39, s54
	v_or_b32_e32 v50, 0x400, v2
	v_or_b32_e32 v59, 0x500, v2
	v_or_b32_e32 v2, v56, v91
	s_addc_u32 s1, s78, s55
	v_and_or_b32 v55, v1, 14, s34
	v_lshl_add_u64 v[0:1], s[0:1], 0, v[2:3]
	v_add_co_u32_e32 v0, vcc, s63, v0
	s_lshl_b32 s8, s41, 7
	s_nop 0
	v_addc_co_u32_e32 v1, vcc, 0, v1, vcc
	global_load_dwordx4 v[44:47], v[0:1], off
	global_load_dwordx4 v[40:43], v[0:1], off offset:64
	v_lshl_add_u32 v0, v54, 1, 0
	v_add_u32_e32 v1, s8, v48
	v_mul_lo_u32 v51, v48, s60
	v_mad_u64_u32 v[48:49], s[6:7], v1, s61, v[0:1]
	v_add_u32_e32 v1, s8, v57
	v_mad_u64_u32 v[0:1], s[6:7], v1, s61, v[0:1]
	v_lshlrev_b32_e32 v1, 2, v54
	s_cmp_eq_u32 s54, 0
	v_mul_lo_u32 v58, v57, s60
	v_add_u32_e32 v57, 0, v1
	s_cselect_b64 s[6:7], -1, 0
	s_add_i32 s10, 0, 0x1f000
	v_cmp_gt_i32_e32 vcc, 3, v55
	ds_write_b128 v48, v[4:7]
	ds_write_b128 v0, v[8:11]
	v_add_lshl_u32 v70, v50, v58, 1
	v_add_lshl_u32 v72, v59, v58, 1
	ds_write_b128 v48, v[12:15] offset:36864
	ds_write_b128 v0, v[16:19] offset:36864
	v_add_u32_e32 v0, 0x1f400, v57
	v_add_u32_e32 v58, s10, v1
	s_and_b64 s[8:9], s[6:7], vcc
	v_cmp_gt_i32_e32 vcc, 2, v55
	ds_read_b128 v[4:7], v0
	ds_read_b128 v[8:11], v0 offset:16
	s_waitcnt vmcnt(10)
	v_cndmask_b32_e64 v64, v31, 0, s[8:9]
	v_cndmask_b32_e64 v65, v30, 0, s[8:9]
	v_cndmask_b32_e64 v66, v29, 0, s[8:9]
	v_cndmask_b32_e64 v63, v28, 0, s[8:9]
	ds_read_b128 v[12:15], v58
	ds_read_b128 v[16:19], v58 offset:16
	s_and_b64 s[8:9], s[6:7], vcc
	v_cmp_gt_i32_e32 vcc, 1, v55
	s_waitcnt vmcnt(8)
	v_cndmask_b32_e64 v67, v27, 0, s[8:9]
	v_cndmask_b32_e64 v68, v26, 0, s[8:9]
	v_cndmask_b32_e64 v69, v25, 0, s[8:9]
	v_cndmask_b32_e64 v71, v24, 0, s[8:9]
	ds_read_b128 v[24:27], v58 offset:256
	ds_read_b128 v[28:31], v58 offset:272
	s_and_b64 s[8:9], s[6:7], vcc
	v_add_lshl_u32 v2, v50, v51, 1
	v_add_lshl_u32 v0, v59, v51, 1
	s_waitcnt vmcnt(7)
	v_cndmask_b32_e64 v73, v39, 0, s[8:9]
	v_cndmask_b32_e64 v89, v38, 0, s[8:9]
	v_cndmask_b32_e64 v83, v37, 0, s[8:9]
	v_cndmask_b32_e64 v77, v36, 0, s[8:9]
	ds_read_b128 v[36:39], v58 offset:512
	ds_read_b128 v[48:51], v58 offset:528
	v_lshlrev_b32_e32 v62, 16, v63
	v_and_b32_e32 v63, 0xffff0000, v63
	s_waitcnt lgkmcnt(5)
	v_pk_fma_f32 v[62:63], v[12:13], v[62:63], v[4:5]
	v_lshlrev_b32_e32 v74, 16, v71
	v_and_b32_e32 v75, 0xffff0000, v71
	s_waitcnt lgkmcnt(3)
	v_pk_fma_f32 v[62:63], v[24:25], v[74:75], v[62:63]
	v_lshlrev_b32_e32 v76, 16, v77
	v_and_b32_e32 v77, 0xffff0000, v77
	s_waitcnt lgkmcnt(1)
	v_pk_fma_f32 v[36:37], v[36:37], v[76:77], v[62:63]
	v_lshlrev_b32_e32 v62, 16, v66
	v_and_b32_e32 v63, 0xffff0000, v66
	v_pk_fma_f32 v[62:63], v[14:15], v[62:63], v[6:7]
	v_lshlrev_b32_e32 v80, 16, v69
	v_and_b32_e32 v81, 0xffff0000, v69
	v_pk_fma_f32 v[62:63], v[26:27], v[80:81], v[62:63]
	v_lshlrev_b32_e32 v82, 16, v83
	v_and_b32_e32 v83, 0xffff0000, v83
	v_pk_fma_f32 v[38:39], v[38:39], v[82:83], v[62:63]
	v_lshlrev_b32_e32 v62, 16, v65
	v_and_b32_e32 v63, 0xffff0000, v65
	v_pk_fma_f32 v[62:63], v[16:17], v[62:63], v[8:9]
	v_lshlrev_b32_e32 v86, 16, v68
	v_and_b32_e32 v87, 0xffff0000, v68
	v_pk_fma_f32 v[62:63], v[28:29], v[86:87], v[62:63]
	v_lshlrev_b32_e32 v102, 16, v89
	v_and_b32_e32 v103, 0xffff0000, v89
	s_waitcnt lgkmcnt(0)
	v_pk_fma_f32 v[48:49], v[48:49], v[102:103], v[62:63]
	v_lshlrev_b32_e32 v62, 16, v64
	v_and_b32_e32 v63, 0xffff0000, v64
	v_pk_fma_f32 v[62:63], v[18:19], v[62:63], v[10:11]
	v_lshlrev_b32_e32 v108, 16, v67
	v_and_b32_e32 v109, 0xffff0000, v67
	s_and_b64 s[8:9], s[80:81], s[6:7]
	v_pk_fma_f32 v[62:63], v[30:31], v[108:109], v[62:63]
	v_lshlrev_b32_e32 v110, 16, v73
	v_and_b32_e32 v111, 0xffff0000, v73
	v_add_u32_e32 v57, 0x1f200, v57
	s_waitcnt vmcnt(5)
	v_cndmask_b32_e64 v105, v35, 0, s[8:9]
	v_cndmask_b32_e64 v107, v34, 0, s[8:9]
	v_cndmask_b32_e64 v85, v33, 0, s[8:9]
	v_cndmask_b32_e64 v79, v32, 0, s[8:9]
	ds_read_b128 v[32:35], v58 offset:768
	ds_read_b128 v[58:61], v58 offset:784
	v_pk_fma_f32 v[50:51], v[50:51], v[110:111], v[62:63]
	ds_read_b128 v[62:65], v57
	ds_read_b128 v[66:69], v57 offset:16
	v_cmp_gt_i32_e32 vcc, -1, v55
	s_and_b64 s[6:7], s[6:7], vcc
	v_pk_fma_f32 v[4:5], v[12:13], v[74:75], v[4:5]
	v_lshlrev_b32_e32 v78, 16, v79
	v_and_b32_e32 v79, 0xffff0000, v79
	s_waitcnt vmcnt(3)
	v_cndmask_b32_e64 v20, v20, 0, s[6:7]
	v_pk_fma_f32 v[4:5], v[24:25], v[76:77], v[4:5]
	v_pk_fma_f32 v[10:11], v[18:19], v[108:109], v[10:11]
	v_pk_fma_f32 v[8:9], v[16:17], v[86:87], v[8:9]
	v_pk_fma_f32 v[6:7], v[14:15], v[80:81], v[6:7]
	s_waitcnt lgkmcnt(1)
	v_pk_fma_f32 v[4:5], v[62:63], v[78:79], v[4:5]
	v_lshlrev_b32_e32 v12, 16, v20
	v_and_b32_e32 v13, 0xffff0000, v20
	v_lshlrev_b32_e32 v84, 16, v85
	v_and_b32_e32 v85, 0xffff0000, v85
	v_lshlrev_b32_e32 v106, 16, v107
	v_and_b32_e32 v107, 0xffff0000, v107
	v_lshlrev_b32_e32 v112, 16, v105
	v_and_b32_e32 v113, 0xffff0000, v105
	v_cndmask_b32_e64 v21, v21, 0, s[6:7]
	v_cndmask_b32_e64 v22, v22, 0, s[6:7]
	v_cndmask_b32_e64 v23, v23, 0, s[6:7]
	v_pk_fma_f32 v[10:11], v[30:31], v[110:111], v[10:11]
	v_pk_fma_f32 v[8:9], v[28:29], v[102:103], v[8:9]
	v_pk_fma_f32 v[6:7], v[26:27], v[82:83], v[6:7]
	v_pk_fma_f32 v[4:5], v[32:33], v[12:13], v[4:5]
	v_mul_lo_u32 v12, v55, s64
	v_pk_fma_f32 v[36:37], v[32:33], v[78:79], v[36:37]
	v_pk_fma_f32 v[38:39], v[34:35], v[84:85], v[38:39]
	s_waitcnt lgkmcnt(0)
	v_pk_fma_f32 v[10:11], v[68:69], v[112:113], v[10:11]
	v_lshlrev_b32_e32 v18, 16, v23
	v_and_b32_e32 v19, 0xffff0000, v23
	v_pk_fma_f32 v[8:9], v[66:67], v[106:107], v[8:9]
	v_lshlrev_b32_e32 v16, 16, v22
	v_and_b32_e32 v17, 0xffff0000, v22
	v_pk_fma_f32 v[6:7], v[64:65], v[84:85], v[6:7]
	v_lshlrev_b32_e32 v14, 16, v21
	v_and_b32_e32 v15, 0xffff0000, v21
	v_add3_u32 v1, s65, v12, v1
	v_pk_fma_f32 v[48:49], v[58:59], v[106:107], v[48:49]
	v_pk_fma_f32 v[50:51], v[60:61], v[112:113], v[50:51]
	v_pk_fma_f32 v[10:11], v[60:61], v[18:19], v[10:11]
	v_pk_fma_f32 v[8:9], v[58:59], v[16:17], v[8:9]
	v_pk_fma_f32 v[6:7], v[34:35], v[14:15], v[6:7]
	ds_write_b128 v1, v[36:39]
	ds_write_b128 v1, v[48:51] offset:16
	ds_write_b128 v1, v[4:7] offset:272
	ds_write_b128 v1, v[8:11] offset:288
	v_lshl_add_u64 v[4:5], s[0:1], 0, v[2:3]
	v_add_co_u32_e32 v4, vcc, s66, v4
	v_mov_b32_e32 v71, v3
	s_nop 0
	v_addc_co_u32_e32 v5, vcc, 0, v5, vcc
	v_lshl_add_u64 v[6:7], s[0:1], 0, v[70:71]
	v_add_co_u32_e32 v8, vcc, s66, v6
	v_mov_b32_e32 v1, v3
	s_nop 0
	v_addc_co_u32_e32 v9, vcc, 0, v7, vcc
	v_lshl_add_u64 v[0:1], s[0:1], 0, v[0:1]
	v_add_co_u32_e32 v0, vcc, s66, v0
	v_mov_b32_e32 v73, v3
	s_nop 0
	v_addc_co_u32_e32 v1, vcc, 0, v1, vcc
	v_lshl_add_u64 v[12:13], s[0:1], 0, v[72:73]
	v_add_co_u32_e32 v16, vcc, s66, v12
	global_load_dwordx4 v[4:7], v[4:5], off
	s_nop 0
	global_load_dwordx4 v[8:11], v[8:9], off
	v_addc_co_u32_e32 v17, vcc, 0, v13, vcc
	global_load_dwordx4 v[12:15], v[0:1], off
	s_nop 0
	global_load_dwordx4 v[16:19], v[16:17], off
	v_mul_lo_u32 v0, v90, s64
	v_add_u32_e32 v102, s65, v0
	s_waitcnt lgkmcnt(0)
	v_lshl_add_u32 v0, v88, 5, v102
	ds_read_b128 v[20:23], v0
	ds_read_b128 v[24:27], v0 offset:16
	v_mul_u32_u24_e32 v1, 0x48, v101
	v_lshlrev_b32_e32 v1, 1, v1
	v_readlane_b32 s0, v254, 49
	s_waitcnt lgkmcnt(1)
	v_cvt_pk_bf16_f32 v20, v20, v21
	v_cvt_pk_bf16_f32 v21, v22, v23
	v_add3_u32 v2, s0, v91, v1
	v_readlane_b32 s0, v254, 52
	s_waitcnt lgkmcnt(0)
	v_cvt_pk_bf16_f32 v22, v24, v25
	v_cvt_pk_bf16_f32 v23, v26, v27
	ds_read_b128 v[24:27], v2
	ds_read_b128 v[28:31], v2 offset:64
	v_add3_u32 v1, s0, v91, v1
	ds_read_b128 v[32:35], v1
	ds_read_b128 v[36:39], v1 offset:64
	ds_read_b128 v[48:51], v2 offset:2304
	ds_read_b128 v[58:61], v2 offset:2368
	ds_read_b128 v[62:65], v1 offset:2304
	ds_read_b128 v[66:69], v1 offset:2368
	ds_read_b128 v[70:73], v2 offset:4608
	ds_read_b128 v[74:77], v2 offset:4672
	ds_read_b128 v[78:81], v1 offset:4608
	ds_read_b128 v[82:85], v1 offset:4672
	ds_read_b128 v[106:109], v2 offset:6912
	ds_read_b128 v[110:113], v1 offset:6912
	ds_read_b128 v[114:117], v2 offset:6976
	ds_read_b128 v[118:121], v0 offset:128
	ds_read_b128 v[122:125], v0 offset:144
	ds_read_b128 v[126:129], v1 offset:6976
	s_waitcnt lgkmcnt(14)
	v_mfma_f32_16x16x32_bf16 v[24:27], v[20:23], v[24:27], 0
	v_lshlrev_b32_e32 v103, 2, v88
	v_or_b32_e32 v105, s34, v103
	v_or_b32_e32 v0, s40, v88
	v_mfma_f32_16x16x32_bf16 v[32:35], v[20:23], v[32:35], 0
	v_lshlrev_b32_e32 v89, 2, v101
	v_cmp_eq_u32_e32 vcc, 0, v0
	v_add_u32_e32 v2, s10, v89
	s_waitcnt lgkmcnt(13)
	v_mfma_f32_16x16x32_bf16 v[48:51], v[20:23], v[48:51], 0
	v_add_u32_e32 v0, s65, v89
	v_readlane_b32 s6, v255, 14
	v_readlane_b32 s7, v255, 15
	s_waitcnt lgkmcnt(11)
	v_mfma_f32_16x16x32_bf16 v[62:65], v[20:23], v[62:65], 0
	s_and_b64 s[6:7], s[6:7], vcc
	v_readlane_b32 s8, v255, 16
	v_cmp_eq_u32_e64 s[0:1], 0, v88
	s_waitcnt lgkmcnt(9)
	v_mfma_f32_16x16x32_bf16 v[70:73], v[20:23], v[70:73], 0
	s_waitcnt lgkmcnt(7)
	v_mfma_f32_16x16x32_bf16 v[78:81], v[20:23], v[78:81], 0
	s_waitcnt lgkmcnt(5)
	v_mfma_f32_16x16x32_bf16 v[106:109], v[20:23], v[106:109], 0
	s_waitcnt lgkmcnt(4)
	v_mfma_f32_16x16x32_bf16 v[20:23], v[20:23], v[110:113], 0
	s_waitcnt lgkmcnt(2)
	v_cvt_pk_bf16_f32 v110, v118, v119
	v_cvt_pk_bf16_f32 v111, v120, v121
	s_waitcnt lgkmcnt(1)
	v_cvt_pk_bf16_f32 v112, v122, v123
	v_cvt_pk_bf16_f32 v113, v124, v125
	s_nop 1
	v_mfma_f32_16x16x32_bf16 v[118:121], v[110:113], v[28:31], v[24:27]
	v_mfma_f32_16x16x32_bf16 v[122:125], v[110:113], v[36:39], v[32:35]
	v_mfma_f32_16x16x32_bf16 v[48:51], v[110:113], v[58:61], v[48:51]
	v_mul_lo_u32 v58, v105, s64
	v_add_u32_e32 v59, 0x110, v58
	v_add_u32_e32 v60, 0x220, v58
	v_add_u32_e32 v61, 0x330, v58
	v_mfma_f32_16x16x32_bf16 v[36:39], v[110:113], v[66:69], v[62:65]
	v_add_u32_e32 v57, v0, v59
	v_mfma_f32_16x16x32_bf16 v[32:35], v[110:113], v[74:77], v[70:73]
	v_add_u32_e32 v76, v0, v60
	v_add_u32_e32 v77, v0, v61
	v_mfma_f32_16x16x32_bf16 v[24:27], v[110:113], v[114:117], v[106:109]
	s_nop 2
	v_add_u32_e32 v106, v0, v58
	ds_read2st64_b32 v[0:1], v2 offset0:5 offset1:6
	ds_read_b32 v2, v2 offset:1792
	ds_read_b32 v62, v106
	ds_read_b32 v63, v57
	ds_read_b32 v64, v76
	ds_read_b32 v65, v77
	s_waitcnt lgkmcnt(5)
	v_fmamk_f32 v67, v122, 0xbfb8aa3b, v1
	v_fmamk_f32 v68, v119, 0xbfb8aa3b, v0
	v_exp_f32_e32 v67, v67
	v_exp_f32_e32 v69, v68
	v_fmamk_f32 v68, v123, 0xbfb8aa3b, v1
	v_exp_f32_e32 v70, v68
	v_fmamk_f32 v66, v118, 0xbfb8aa3b, v0
	v_add_f32_e32 v67, 1.0, v67
	v_exp_f32_e32 v66, v66
	v_rcp_f32_e32 v68, v67
	v_add_f32_e32 v67, 1.0, v69
	v_add_f32_e32 v69, 1.0, v70
	v_fmamk_f32 v70, v120, 0xbfb8aa3b, v0
	v_fmamk_f32 v0, v121, 0xbfb8aa3b, v0
	v_exp_f32_e32 v70, v70
	v_fmamk_f32 v71, v124, 0xbfb8aa3b, v1
	v_exp_f32_e32 v0, v0
	v_exp_f32_e32 v71, v71
	v_add_f32_e32 v66, 1.0, v66
	v_rcp_f32_e32 v66, v66
	v_rcp_f32_e32 v67, v67
	v_add_f32_e32 v70, 1.0, v70
	v_add_f32_e32 v0, 1.0, v0
	v_rcp_f32_e32 v70, v70
	v_add_f32_e32 v72, 1.0, v71
	v_rcp_f32_e32 v71, v0
	v_fmac_f32_e32 v1, 0xbfb8aa3b, v125
	s_waitcnt lgkmcnt(4)
	v_pk_mul_f32 v[66:67], v[2:3], v[66:67] op_sel_hi:[0,1]
	v_exp_f32_e32 v73, v1
	v_pk_mul_f32 v[0:1], v[2:3], v[70:71] op_sel_hi:[0,1]
	v_exp_f32_e32 v74, v66
	v_exp_f32_e32 v75, v67
	v_exp_f32_e32 v0, v0
	v_exp_f32_e32 v1, v1
	v_add_f32_e32 v2, 1.0, v73
	v_pk_mul_f32 v[70:71], v[74:75], v[74:75]
	v_rcp_f32_e32 v73, v2
	v_pk_mul_f32 v[66:67], v[0:1], v[0:1]
	v_sub_f32_e32 v2, 1.0, v70
	v_sqrt_f32_e32 v2, v2
	v_sub_f32_e32 v70, 1.0, v71
	v_sub_f32_e32 v66, 1.0, v66
	v_sub_f32_e32 v67, 1.0, v67
	v_rcp_f32_e32 v69, v69
	v_rcp_f32_e32 v72, v72
	v_sqrt_f32_e32 v71, v70
	v_sqrt_f32_e32 v66, v66
	v_sqrt_f32_e32 v67, v67
	v_cndmask_b32_e64 v70, v2, 1.0, s[6:7]
	v_pk_mul_f32 v[68:69], v[68:69], v[70:71]
	v_mfma_f32_16x16x32_bf16 v[28:31], v[110:113], v[82:85], v[78:81]
	v_mul_f32_e64 v66, v72, v66
	v_mul_f32_e64 v67, v73, v67
	s_waitcnt lgkmcnt(0)
	v_pk_mul_f32 v[64:65], v[64:65], v[66:67]
	v_pk_mul_f32 v[66:67], v[62:63], v[68:69]
	ds_write_b32 v57, v67
	v_fma_f32 v2, 0, v74, v66
	v_fmac_f32_e32 v67, v75, v2
	v_mul_f32_e32 v2, v75, v74
	v_and_or_b32 v78, v95, 64, v101
	v_fma_f32 v57, v0, v67, v64
	v_mul_f32_e32 v2, v0, v2
	ds_write_b32 v77, v65
	v_fmac_f32_e32 v65, v1, v57
	v_mul_f32_e32 v57, v1, v2
	v_lshlrev_b32_e32 v2, 2, v78
	ds_bpermute_b32 v122, v2, v57
	ds_bpermute_b32 v136, v2, v65
	ds_bpermute_b32 v123, v2, v57 offset:64
	ds_bpermute_b32 v132, v2, v65 offset:64
	ds_bpermute_b32 v120, v2, v57 offset:128
	ds_bpermute_b32 v131, v2, v65 offset:128
	ds_bpermute_b32 v62, v2, v57 offset:192
	ds_bpermute_b32 v63, v2, v65 offset:192
	v_mfma_f32_16x16x32_bf16 v[20:23], v[110:113], v[126:129], v[20:23]
	s_waitcnt lgkmcnt(6)
	v_fmac_f32_e32 v136, 0, v122
	v_lshl_add_u32 v57, v101, 2, s8
	ds_write_b32 v106, v66
	ds_write_b32 v76, v64
	s_and_saveexec_b64 s[8:9], s[0:1]
	s_cbranch_execz .LBB0_211
	s_waitcnt lgkmcnt(7)
	v_mul_f32_e32 v64, v122, v123
	s_waitcnt lgkmcnt(6)
	v_fma_f32 v65, v136, v123, v132
	s_waitcnt lgkmcnt(5)
	v_mul_f32_e32 v64, v64, v120
	s_waitcnt lgkmcnt(4)
	v_fma_f32 v65, v65, v120, v131
	s_waitcnt lgkmcnt(3)
	v_mul_f32_e32 v64, v64, v62
	s_waitcnt lgkmcnt(2)
	v_fmac_f32_e32 v63, v65, v62
	ds_write2st64_b32 v57, v64, v63 offset1:8

.LBB0_217:
	s_or_b64 exec, exec, s[6:7]
	s_waitcnt lgkmcnt(2)
	v_lshlrev_b32_e32 v2, 3, v88
	v_readlane_b32 s6, v255, 10
	v_add_u32_e32 v30, v56, v2
	v_add_u32_e32 v2, 0x1c00, v30
	v_or_b32_e32 v21, s6, v54
	s_add_u32 s6, s39, s54
	s_addc_u32 s7, s78, s55
	v_lshl_add_u64 v[22:23], s[6:7], 0, v[2:3]
	v_add_u32_e32 v2, 0x1400, v30
	v_add_co_u32_e32 v22, vcc, s63, v22
	v_lshl_add_u64 v[24:25], s[6:7], 0, v[2:3]
	s_nop 0
	v_addc_co_u32_e32 v23, vcc, 0, v23, vcc
	v_add_co_u32_e32 v24, vcc, s63, v24
	v_add_u32_e32 v2, 0x1420, v30
	s_nop 0
	v_addc_co_u32_e32 v25, vcc, 0, v25, vcc
	v_lshl_add_u64 v[26:27], s[6:7], 0, v[2:3]
	v_add_co_u32_e32 v26, vcc, s63, v26
	v_add_u32_e32 v2, 0x1440, v30
	s_nop 0
	v_addc_co_u32_e32 v27, vcc, 0, v27, vcc
	v_lshl_add_u64 v[28:29], s[6:7], 0, v[2:3]
	s_waitcnt lgkmcnt(0)
	s_barrier
	v_add_co_u32_e32 v28, vcc, s63, v28
	v_add_u32_e32 v2, 0x1460, v30
	v_mul_lo_u32 v20, v55, s60
	v_addc_co_u32_e32 v29, vcc, 0, v29, vcc
	global_load_dwordx2 v[68:69], v[22:23], off
	global_load_dwordx2 v[62:63], v[22:23], off offset:32
	global_load_dwordx2 v[56:57], v[22:23], off offset:64
	global_load_dwordx2 v[48:49], v[22:23], off offset:96
	global_load_dwordx2 v[70:71], v[22:23], off offset:2048
	global_load_dwordx2 v[64:65], v[22:23], off offset:2080
	global_load_dwordx2 v[58:59], v[22:23], off offset:2112
	global_load_dwordx2 v[50:51], v[22:23], off offset:2144
	v_lshl_add_u64 v[22:23], s[6:7], 0, v[2:3]
	v_add_lshl_u32 v20, v21, v20, 1
	v_add_co_u32_e32 v22, vcc, s63, v22
	v_mov_b32_e32 v21, v3
	s_nop 0
	v_addc_co_u32_e32 v23, vcc, 0, v23, vcc
	v_lshl_add_u64 v[20:21], s[6:7], 0, v[20:21]
	s_mov_b32 s6, 0x9f57000
	global_load_dwordx2 v[72:73], v[24:25], off
	global_load_dwordx2 v[66:67], v[26:27], off
	global_load_dwordx2 v[60:61], v[28:29], off
	global_load_dwordx2 v[54:55], v[22:23], off
	s_lshl_b32 s6, s41, 8
	s_add_i32 s6, s6, 0
	s_mov_b32 s101, 0
	v_cmp_lt_u32_e64 s[20:21], 1, v88
	v_cmp_eq_u32_e64 s[22:23], 3, v88
	v_add_u32_e32 v2, s6, v89
	v_add_u32_e32 v2, 0x20800, v2
	v_add_u32_e32 v32, 0x1f800, v89
	ds_read_b32 v216, v2
	ds_read_b32 v217, v2 offset:64
	ds_read_b32 v218, v2 offset:128
	ds_read_b32 v219, v2 offset:192
	v_add_u32_e32 v33, 64, v32
	v_add_u32_e32 v34, 0x80, v32
	v_add_u32_e32 v35, 0xc0, v32
	ds_read2st64_b32 v[160:161], v32 offset1:8
	ds_read2st64_b32 v[162:163], v33 offset1:8
	ds_read2st64_b32 v[164:165], v34 offset1:8
	ds_read2st64_b32 v[166:167], v35 offset1:8
	ds_read2st64_b32 v[168:169], v32 offset0:1 offset1:9
	ds_read2st64_b32 v[170:171], v33 offset0:1 offset1:9
	ds_read2st64_b32 v[172:173], v34 offset0:1 offset1:9
	ds_read2st64_b32 v[174:175], v35 offset0:1 offset1:9
	ds_read2st64_b32 v[176:177], v32 offset0:2 offset1:10
	ds_read2st64_b32 v[178:179], v33 offset0:2 offset1:10
	ds_read2st64_b32 v[180:181], v34 offset0:2 offset1:10
	ds_read2st64_b32 v[182:183], v35 offset0:2 offset1:10
	ds_read2st64_b32 v[184:185], v32 offset0:3 offset1:11
	ds_read2st64_b32 v[186:187], v33 offset0:3 offset1:11
	ds_read2st64_b32 v[188:189], v34 offset0:3 offset1:11
	ds_read2st64_b32 v[190:191], v35 offset0:3 offset1:11
	ds_read2st64_b32 v[192:193], v32 offset0:4 offset1:12
	ds_read2st64_b32 v[194:195], v33 offset0:4 offset1:12
	ds_read2st64_b32 v[196:197], v34 offset0:4 offset1:12
	ds_read2st64_b32 v[198:199], v35 offset0:4 offset1:12
	ds_read2st64_b32 v[200:201], v32 offset0:5 offset1:13
	ds_read2st64_b32 v[202:203], v33 offset0:5 offset1:13
	ds_read2st64_b32 v[204:205], v34 offset0:5 offset1:13
	ds_read2st64_b32 v[206:207], v35 offset0:5 offset1:13
	ds_read2st64_b32 v[208:209], v32 offset0:6 offset1:14
	ds_read2st64_b32 v[210:211], v33 offset0:6 offset1:14
	ds_read2st64_b32 v[212:213], v34 offset0:6 offset1:14
	ds_read2st64_b32 v[214:215], v35 offset0:6 offset1:14
	ds_read2_b32 v[220:221], v106 offset1:68
	ds_read2_b32 v[222:223], v106 offset0:136 offset1:204
	ds_read2_b32 v[224:225], v106 offset0:16 offset1:84
	ds_read2_b32 v[226:227], v106 offset0:152 offset1:220
	ds_read2_b32 v[230:231], v106 offset0:32 offset1:100
	ds_read2_b32 v[232:233], v106 offset0:168 offset1:236
	ds_read2_b32 v[234:235], v106 offset0:48 offset1:116
	ds_read2_b32 v[236:237], v106 offset0:184 offset1:252
	s_xor_b32 s96, s41, 1
	v_readlane_b32 s56, v255, 17
	v_readlane_b32 s57, v255, 18
	s_lshl_b32 s58, s96, 8
	s_add_i32 s58, s58, 0x20800
	v_add_u32_e32 v31, s58, v89
	s_and_b64 s[56:57], s[56:57], s[22:23]
	v_cndmask_b32_e64 v22, v136, 0, s[0:1]
	v_cndmask_b32_e64 v23, v122, 1.0, s[0:1]
	v_fmac_f32_e32 v132, v22, v123
	v_mul_f32_e32 v30, v23, v123
	v_cndmask_b32_e64 v22, v22, v132, s[20:21]
	v_cndmask_b32_e64 v23, v23, v30, s[20:21]
	v_fmac_f32_e32 v131, v22, v120
	v_mul_f32_e32 v30, v23, v120
	v_cndmask_b32_e64 v22, v22, v131, s[22:23]
	v_cndmask_b32_e64 v23, v23, v30, s[22:23]
	v_cndmask_b32_e64 v24, v130, 0, s[0:1]
	v_cndmask_b32_e64 v25, v126, 1.0, s[0:1]
	v_fmac_f32_e32 v129, v24, v128
	v_mul_f32_e32 v30, v25, v128
	v_cndmask_b32_e64 v24, v24, v129, s[20:21]
	v_cndmask_b32_e64 v25, v25, v30, s[20:21]
	v_fmac_f32_e32 v125, v24, v124
	v_mul_f32_e32 v30, v25, v124
	v_cndmask_b32_e64 v24, v24, v125, s[22:23]
	v_cndmask_b32_e64 v25, v25, v30, s[22:23]
	v_cndmask_b32_e64 v26, v139, 0, s[0:1]
	v_cndmask_b32_e64 v27, v135, 1.0, s[0:1]
	v_fmac_f32_e32 v138, v26, v137
	v_mul_f32_e32 v30, v27, v137
	v_cndmask_b32_e64 v26, v26, v138, s[20:21]
	v_cndmask_b32_e64 v27, v27, v30, s[20:21]
	v_fmac_f32_e32 v134, v26, v133
	v_mul_f32_e32 v30, v27, v133
	v_cndmask_b32_e64 v26, v26, v134, s[22:23]
	v_cndmask_b32_e64 v27, v27, v30, s[22:23]
	v_cndmask_b32_e64 v28, v146, 0, s[0:1]
	v_cndmask_b32_e64 v29, v142, 1.0, s[0:1]
	v_fmac_f32_e32 v145, v28, v143
	v_mul_f32_e32 v30, v29, v143
	v_cndmask_b32_e64 v28, v28, v145, s[20:21]
	v_cndmask_b32_e64 v29, v29, v30, s[20:21]
	v_fmac_f32_e32 v141, v28, v140
	v_mul_f32_e32 v30, v29, v140
	v_cndmask_b32_e64 v28, v28, v141, s[22:23]
	v_cndmask_b32_e64 v29, v29, v30, s[22:23]
	s_waitcnt lgkmcnt(15)
	s_andn2_b64 vcc, exec, s[82:83]
	s_cbranch_vccnz .Lb4_fold_done
	v_fma_f32 v216, v160, v216, v161
	v_fma_f32 v217, v162, v217, v163
	v_fma_f32 v218, v164, v218, v165
	v_fma_f32 v219, v166, v219, v167
	s_andn2_b64 vcc, exec, s[84:85]
	s_cbranch_vccnz .Lb4_fold_done
	v_fma_f32 v216, v168, v216, v169
	v_fma_f32 v217, v170, v217, v171
	v_fma_f32 v218, v172, v218, v173
	v_fma_f32 v219, v174, v219, v175
	s_andn2_b64 vcc, exec, s[86:87]
	s_cbranch_vccnz .Lb4_fold_done
	v_fma_f32 v216, v176, v216, v177
	v_fma_f32 v217, v178, v217, v179
	v_fma_f32 v218, v180, v218, v181
	v_fma_f32 v219, v182, v219, v183
	s_andn2_b64 vcc, exec, s[88:89]
	s_cbranch_vccnz .Lb4_fold_done
	v_fma_f32 v216, v184, v216, v185
	v_fma_f32 v217, v186, v217, v187
	v_fma_f32 v218, v188, v218, v189
	v_fma_f32 v219, v190, v219, v191
	s_andn2_b64 vcc, exec, s[90:91]
	s_cbranch_vccnz .Lb4_fold_done
	v_fma_f32 v216, v192, v216, v193
	v_fma_f32 v217, v194, v217, v195
	v_fma_f32 v218, v196, v218, v197
	v_fma_f32 v219, v198, v219, v199
	s_waitcnt lgkmcnt(8)
	s_andn2_b64 vcc, exec, s[92:93]
	s_cbranch_vccnz .Lb4_fold_done
	v_fma_f32 v216, v200, v216, v201
	v_fma_f32 v217, v202, v217, v203
	v_fma_f32 v218, v204, v218, v205
	v_fma_f32 v219, v206, v219, v207
	s_andn2_b64 vcc, exec, s[94:95]
	s_cbranch_vccnz .Lb4_fold_done
	v_fma_f32 v216, v208, v216, v209
	v_fma_f32 v217, v210, v217, v211
	v_fma_f32 v218, v212, v218, v213
	v_fma_f32 v219, v214, v219, v215
.Lb4_fold_done:
	v_fmac_f32_e32 v22, v23, v216
	v_fmac_f32_e32 v24, v25, v217
	v_fmac_f32_e32 v26, v27, v218
	v_fmac_f32_e32 v28, v29, v219
	s_waitcnt lgkmcnt(0)
	v_fma_f32 v220, v74, v22, v220
	v_fmac_f32_e32 v221, v75, v220
	v_fma_f32 v222, v0, v221, v222
	v_fmac_f32_e32 v223, v1, v222
	v_fma_f32 v224, v78, v24, v224
	v_fmac_f32_e32 v225, v79, v224
	v_fma_f32 v226, v76, v225, v226
	v_fmac_f32_e32 v227, v77, v226
	v_fma_f32 v230, v82, v26, v230
	v_fmac_f32_e32 v231, v83, v230
	v_fma_f32 v232, v80, v231, v232
	v_fmac_f32_e32 v233, v81, v232
	v_fma_f32 v234, v86, v28, v234
	v_fmac_f32_e32 v235, v87, v234
	v_fma_f32 v236, v84, v235, v236
	v_fmac_f32_e32 v237, v85, v236
	ds_write2_b32 v106, v220, v221 offset1:68
	ds_write2_b32 v106, v222, v223 offset0:136 offset1:204
	ds_write2_b32 v106, v224, v225 offset0:16 offset1:84
	ds_write2_b32 v106, v226, v227 offset0:152 offset1:220
	ds_write2_b32 v106, v230, v231 offset0:32 offset1:100
	ds_write2_b32 v106, v232, v233 offset0:168 offset1:236
	ds_write2_b32 v106, v234, v235 offset0:48 offset1:116
	ds_write2_b32 v106, v236, v237 offset0:184 offset1:252
	s_and_saveexec_b64 s[58:59], s[56:57]
	ds_write_b32 v31, v223
	ds_write_b32 v31, v227 offset:64
	ds_write_b32 v31, v233 offset:128
	ds_write_b32 v31, v237 offset:192
	s_or_b64 exec, exec, s[58:59]
	s_mov_b64 s[0:1], exec
	s_branch .LBB0_208

	.amdhsa_kernel _Z8mega_fwd4Args
		.amdhsa_group_segment_fixed_size 0
		.amdhsa_private_segment_fixed_size 0
		.amdhsa_kernarg_size 448
		.amdhsa_user_sgpr_count 2
		.amdhsa_user_sgpr_dispatch_ptr 0
		.amdhsa_user_sgpr_queue_ptr 0
		.amdhsa_user_sgpr_kernarg_segment_ptr 1
		.amdhsa_user_sgpr_dispatch_id 0
		.amdhsa_user_sgpr_kernarg_preload_length 0
		.amdhsa_user_sgpr_kernarg_preload_offset 0
		.amdhsa_user_sgpr_private_segment_size 0
		.amdhsa_uses_dynamic_stack 0
		.amdhsa_enable_private_segment 0
		.amdhsa_system_sgpr_workgroup_id_x 1
		.amdhsa_system_sgpr_workgroup_id_y 0
		.amdhsa_system_sgpr_workgroup_id_z 0
		.amdhsa_system_sgpr_workgroup_info 0
		.amdhsa_system_vgpr_workitem_id 2
		.amdhsa_next_free_vgpr 256
		.amdhsa_next_free_sgpr 102
		.amdhsa_accum_offset 256
		.amdhsa_reserve_vcc 1
		.amdhsa_float_round_mode_32 0
		.amdhsa_float_round_mode_16_64 0
		.amdhsa_float_denorm_mode_32 3
		.amdhsa_float_denorm_mode_16_64 3
		.amdhsa_dx10_clamp 1
		.amdhsa_ieee_mode 1
		.amdhsa_fp16_overflow 0
		.amdhsa_tg_split 0
		.amdhsa_exception_fp_ieee_invalid_op 0
		.amdhsa_exception_fp_denorm_src 0
		.amdhsa_exception_fp_ieee_div_zero 0
		.amdhsa_exception_fp_ieee_overflow 0
		.amdhsa_exception_fp_ieee_underflow 0
		.amdhsa_exception_fp_ieee_inexact 0
		.amdhsa_exception_int_div_zero 0
	.end_amdhsa_kernel

amdhsa.kernels:
  - .agpr_count:     0
    .args:
      - .offset:         0
        .size:           192
        .value_kind:     by_value
      - .offset:         192
        .size:           4
        .value_kind:     hidden_block_count_x
      - .offset:         196
        .size:           4
        .value_kind:     hidden_block_count_y
      - .offset:         200
        .size:           4
        .value_kind:     hidden_block_count_z
      - .offset:         204
        .size:           2
        .value_kind:     hidden_group_size_x
      - .offset:         206
        .size:           2
        .value_kind:     hidden_group_size_y
      - .offset:         208
        .size:           2
        .value_kind:     hidden_group_size_z
      - .offset:         210
        .size:           2
        .value_kind:     hidden_remainder_x
      - .offset:         212
        .size:           2
        .value_kind:     hidden_remainder_y
      - .offset:         214
        .size:           2
        .value_kind:     hidden_remainder_z
      - .offset:         232
        .size:           8
        .value_kind:     hidden_global_offset_x
      - .offset:         240
        .size:           8
        .value_kind:     hidden_global_offset_y
      - .offset:         248
        .size:           8
        .value_kind:     hidden_global_offset_z
      - .offset:         256
        .size:           2
        .value_kind:     hidden_grid_dims
      - .offset:         280
        .size:           8
        .value_kind:     hidden_multigrid_sync_arg
      - .offset:         312
        .size:           4
        .value_kind:     hidden_dynamic_lds_size
    .group_segment_fixed_size: 0
    .kernarg_segment_align: 8
    .kernarg_segment_size: 448
    .language:       OpenCL C
    .language_version:
      - 2
      - 0
    .max_flat_workgroup_size: 512
    .name:           _Z8mega_fwd4Args
    .private_segment_fixed_size: 0
    .sgpr_count:     108
    .sgpr_spill_count: 86
    .symbol:         _Z8mega_fwd4Args.kd
    .uniform_work_group_size: 1
    .uses_dynamic_stack: false
    .vgpr_count:     256
    .vgpr_spill_count: 0
    .wavefront_size: 64
